# v65 + grid-size guard (gridDim.x != 256 keeps the original epilogue / barrier / P5 path)
# baseline (speedup 1.0000x reference)
.LBB0_791:
	s_cmp_lg_u32 s24, 0x100
	s_cbranch_scc1 .Lp4_orig_epi
	v_lshl_add_u32 v146, s44, 8, v154
	v_lshl_or_b32 v144, s46, 8, v156
	v_xor_b32_e32 v149, 16, v161
	v_xor_b32_e32 v150, 32, v161
	v_lshl_add_u32 v145, v146, 11, v144
	v_lshlrev_b32_e32 v149, 2, v149
	v_lshlrev_b32_e32 v150, 2, v150
	v_lshlrev_b32_e32 v148, 2, v146
	v_lshlrev_b32_e32 v147, 1, v145
	s_mov_b64 s[48:49], s[12:13]
	s_mov_b64 s[50:51], s[14:15]
	global_load_dword v176, v148, s[22:23] offset:0
	global_load_dwordx4 v[184:187], v147, s[48:49] offset:0
	global_load_dwordx4 v[188:191], v147, s[50:51] offset:0
	global_load_dwordx4 v[192:195], v147, s[48:49] offset:256
	global_load_dwordx4 v[196:199], v147, s[50:51] offset:256
	s_add_u32 s48, s12, 0x10000
	s_addc_u32 s49, s13, 0
	s_add_u32 s50, s14, 0x10000
	s_addc_u32 s51, s15, 0
	global_load_dword v177, v148, s[22:23] offset:64
	global_load_dwordx4 v[200:203], v147, s[48:49] offset:0
	global_load_dwordx4 v[204:207], v147, s[50:51] offset:0
	global_load_dwordx4 v[208:211], v147, s[48:49] offset:256
	global_load_dwordx4 v[212:215], v147, s[50:51] offset:256
	s_add_u32 s48, s12, 0x20000
	s_addc_u32 s49, s13, 0
	s_add_u32 s50, s14, 0x20000
	s_addc_u32 s51, s15, 0
	global_load_dword v178, v148, s[22:23] offset:128
	global_load_dwordx4 v[216:219], v147, s[48:49] offset:0
	global_load_dwordx4 v[220:223], v147, s[50:51] offset:0
	global_load_dwordx4 v[226:229], v147, s[48:49] offset:256
	global_load_dwordx4 v[230:233], v147, s[50:51] offset:256
	s_add_u32 s48, s12, 0x30000
	s_addc_u32 s49, s13, 0
	s_add_u32 s50, s14, 0x30000
	s_addc_u32 s51, s15, 0
	global_load_dword v179, v148, s[22:23] offset:192
	global_load_dwordx4 v[234:237], v147, s[48:49] offset:0
	global_load_dwordx4 v[238:241], v147, s[50:51] offset:0
	global_load_dwordx4 v[242:245], v147, s[48:49] offset:256
	global_load_dwordx4 v[246:249], v147, s[50:51] offset:256
	s_waitcnt vmcnt(15)
	v_fmamk_f32 v151, v176, 0x3a000000, v160
	v_mul_f32_e32 v152, 0x4b800000, v151
	v_cmp_gt_f32_e32 vcc, s65, v151
	s_nop 1
	v_cndmask_b32_e32 v151, v151, v152, vcc
	v_rsq_f32_e32 v151, v151
	s_nop 0
	v_mul_f32_e32 v152, 0x45800000, v151
	v_cndmask_b32_e32 v151, v151, v152, vcc
	v_lshlrev_b32_e32 v162, 16, v184
	v_and_b32_e32 v163, 0xffff0000, v184
	v_lshlrev_b32_e32 v170, 16, v188
	v_and_b32_e32 v171, 0xffff0000, v188
	v_lshlrev_b32_e32 v164, 16, v185
	v_and_b32_e32 v165, 0xffff0000, v185
	v_lshlrev_b32_e32 v172, 16, v189
	v_and_b32_e32 v173, 0xffff0000, v189
	v_lshlrev_b32_e32 v166, 16, v186
	v_and_b32_e32 v167, 0xffff0000, v186
	v_lshlrev_b32_e32 v174, 16, v190
	v_and_b32_e32 v175, 0xffff0000, v190
	v_lshlrev_b32_e32 v168, 16, v187
	v_and_b32_e32 v169, 0xffff0000, v187
	v_lshlrev_b32_e32 v180, 16, v191
	v_and_b32_e32 v181, 0xffff0000, v191
	v_mul_f32_e32 v124, v124, v151
	v_mul_f32_e32 v125, v125, v151
	v_mul_f32_e32 v126, v126, v151
	v_mul_f32_e32 v127, v127, v151
	v_mul_f32_e32 v120, v120, v151
	v_mul_f32_e32 v121, v121, v151
	v_mul_f32_e32 v122, v122, v151
	v_mul_f32_e32 v123, v123, v151
	v_mul_f32_e32 v124, 0xbfb8aa3b, v124
	v_mul_f32_e32 v125, 0xbfb8aa3b, v125
	v_mul_f32_e32 v126, 0xbfb8aa3b, v126
	v_mul_f32_e32 v127, 0xbfb8aa3b, v127
	v_mul_f32_e32 v120, 0xbfb8aa3b, v120
	v_mul_f32_e32 v121, 0xbfb8aa3b, v121
	v_mul_f32_e32 v122, 0xbfb8aa3b, v122
	v_mul_f32_e32 v123, 0xbfb8aa3b, v123
	v_exp_f32_e32 v124, v124
	v_exp_f32_e32 v125, v125
	v_exp_f32_e32 v126, v126
	v_exp_f32_e32 v127, v127
	v_exp_f32_e32 v120, v120
	v_exp_f32_e32 v121, v121
	v_exp_f32_e32 v122, v122
	v_exp_f32_e32 v123, v123
	v_add_f32_e32 v124, 1.0, v124
	v_add_f32_e32 v125, 1.0, v125
	v_add_f32_e32 v126, 1.0, v126
	v_add_f32_e32 v127, 1.0, v127
	v_add_f32_e32 v120, 1.0, v120
	v_add_f32_e32 v121, 1.0, v121
	v_add_f32_e32 v122, 1.0, v122
	v_add_f32_e32 v123, 1.0, v123
	v_rcp_f32_e32 v124, v124
	v_rcp_f32_e32 v125, v125
	v_rcp_f32_e32 v126, v126
	v_rcp_f32_e32 v127, v127
	v_rcp_f32_e32 v120, v120
	v_rcp_f32_e32 v121, v121
	v_rcp_f32_e32 v122, v122
	v_rcp_f32_e32 v123, v123
	v_fma_f32 v124, v124, v170, v162
	v_fma_f32 v125, v125, v171, v163
	v_fma_f32 v126, v126, v172, v164
	v_fma_f32 v127, v127, v173, v165
	v_fma_f32 v120, v120, v174, v166
	v_fma_f32 v121, v121, v175, v167
	v_fma_f32 v122, v122, v180, v168
	v_fma_f32 v123, v123, v181, v169
	v_mul_f32_e32 v152, v125, v125
	v_mul_f32_e32 v153, v127, v127
	v_mul_f32_e32 v182, v121, v121
	v_mul_f32_e32 v183, v123, v123
	v_fmac_f32_e32 v152, v124, v124
	v_fmac_f32_e32 v153, v126, v126
	v_fmac_f32_e32 v182, v120, v120
	v_fmac_f32_e32 v183, v122, v122
	v_add_f32_e32 v152, v152, v153
	v_add_f32_e32 v182, v182, v183
	v_add_f32_e32 v224, v152, v182
	v_lshlrev_b32_e32 v162, 16, v192
	v_and_b32_e32 v163, 0xffff0000, v192
	v_lshlrev_b32_e32 v170, 16, v196
	v_and_b32_e32 v171, 0xffff0000, v196
	v_lshlrev_b32_e32 v164, 16, v193
	v_and_b32_e32 v165, 0xffff0000, v193
	v_lshlrev_b32_e32 v172, 16, v197
	v_and_b32_e32 v173, 0xffff0000, v197
	v_lshlrev_b32_e32 v166, 16, v194
	v_and_b32_e32 v167, 0xffff0000, v194
	v_lshlrev_b32_e32 v174, 16, v198
	v_and_b32_e32 v175, 0xffff0000, v198
	v_lshlrev_b32_e32 v168, 16, v195
	v_and_b32_e32 v169, 0xffff0000, v195
	v_lshlrev_b32_e32 v180, 16, v199
	v_and_b32_e32 v181, 0xffff0000, v199
	v_mul_f32_e32 v116, v116, v151
	v_mul_f32_e32 v117, v117, v151
	v_mul_f32_e32 v118, v118, v151
	v_mul_f32_e32 v119, v119, v151
	v_mul_f32_e32 v112, v112, v151
	v_mul_f32_e32 v113, v113, v151
	v_mul_f32_e32 v114, v114, v151
	v_mul_f32_e32 v115, v115, v151
	v_mul_f32_e32 v116, 0xbfb8aa3b, v116
	v_mul_f32_e32 v117, 0xbfb8aa3b, v117
	v_mul_f32_e32 v118, 0xbfb8aa3b, v118
	v_mul_f32_e32 v119, 0xbfb8aa3b, v119
	v_mul_f32_e32 v112, 0xbfb8aa3b, v112
	v_mul_f32_e32 v113, 0xbfb8aa3b, v113
	v_mul_f32_e32 v114, 0xbfb8aa3b, v114
	v_mul_f32_e32 v115, 0xbfb8aa3b, v115
	v_exp_f32_e32 v116, v116
	v_exp_f32_e32 v117, v117
	v_exp_f32_e32 v118, v118
	v_exp_f32_e32 v119, v119
	v_exp_f32_e32 v112, v112
	v_exp_f32_e32 v113, v113
	v_exp_f32_e32 v114, v114
	v_exp_f32_e32 v115, v115
	v_add_f32_e32 v116, 1.0, v116
	v_add_f32_e32 v117, 1.0, v117
	v_add_f32_e32 v118, 1.0, v118
	v_add_f32_e32 v119, 1.0, v119
	v_add_f32_e32 v112, 1.0, v112
	v_add_f32_e32 v113, 1.0, v113
	v_add_f32_e32 v114, 1.0, v114
	v_add_f32_e32 v115, 1.0, v115
	v_rcp_f32_e32 v116, v116
	v_rcp_f32_e32 v117, v117
	v_rcp_f32_e32 v118, v118
	v_rcp_f32_e32 v119, v119
	v_rcp_f32_e32 v112, v112
	v_rcp_f32_e32 v113, v113
	v_rcp_f32_e32 v114, v114
	v_rcp_f32_e32 v115, v115
	v_fma_f32 v116, v116, v170, v162
	v_fma_f32 v117, v117, v171, v163
	v_fma_f32 v118, v118, v172, v164
	v_fma_f32 v119, v119, v173, v165
	v_fma_f32 v112, v112, v174, v166
	v_fma_f32 v113, v113, v175, v167
	v_fma_f32 v114, v114, v180, v168
	v_fma_f32 v115, v115, v181, v169
	v_mul_f32_e32 v152, v117, v117
	v_mul_f32_e32 v153, v119, v119
	v_mul_f32_e32 v182, v113, v113
	v_mul_f32_e32 v183, v115, v115
	v_fmac_f32_e32 v152, v116, v116
	v_fmac_f32_e32 v153, v118, v118
	v_fmac_f32_e32 v182, v112, v112
	v_fmac_f32_e32 v183, v114, v114
	v_add_f32_e32 v152, v152, v153
	v_add_f32_e32 v182, v182, v183
	v_add_f32_e32 v250, v152, v182
	s_add_u32 s48, s12, 0x80000
	s_addc_u32 s49, s13, 0
	s_add_u32 s50, s14, 0x80000
	s_addc_u32 s51, s15, 0
	global_load_dword v176, v148, s[22:23] offset:512
	global_load_dwordx4 v[184:187], v147, s[48:49] offset:0
	global_load_dwordx4 v[188:191], v147, s[50:51] offset:0
	global_load_dwordx4 v[192:195], v147, s[48:49] offset:256
	global_load_dwordx4 v[196:199], v147, s[50:51] offset:256
	v_add_f32_e32 v251, v224, v250
	ds_bpermute_b32 v252, v149, v251
	s_waitcnt vmcnt(15)
	v_fmamk_f32 v151, v177, 0x3a000000, v160
	v_mul_f32_e32 v152, 0x4b800000, v151
	v_cmp_gt_f32_e32 vcc, s65, v151
	s_nop 1
	v_cndmask_b32_e32 v151, v151, v152, vcc
	v_rsq_f32_e32 v151, v151
	s_nop 0
	v_mul_f32_e32 v152, 0x45800000, v151
	v_cndmask_b32_e32 v151, v151, v152, vcc
	v_lshlrev_b32_e32 v162, 16, v200
	v_and_b32_e32 v163, 0xffff0000, v200
	v_lshlrev_b32_e32 v170, 16, v204
	v_and_b32_e32 v171, 0xffff0000, v204
	v_lshlrev_b32_e32 v164, 16, v201
	v_and_b32_e32 v165, 0xffff0000, v201
	v_lshlrev_b32_e32 v172, 16, v205
	v_and_b32_e32 v173, 0xffff0000, v205
	v_lshlrev_b32_e32 v166, 16, v202
	v_and_b32_e32 v167, 0xffff0000, v202
	v_lshlrev_b32_e32 v174, 16, v206
	v_and_b32_e32 v175, 0xffff0000, v206
	v_lshlrev_b32_e32 v168, 16, v203
	v_and_b32_e32 v169, 0xffff0000, v203
	v_lshlrev_b32_e32 v180, 16, v207
	v_and_b32_e32 v181, 0xffff0000, v207
	v_mul_f32_e32 v108, v108, v151
	v_mul_f32_e32 v109, v109, v151
	v_mul_f32_e32 v110, v110, v151
	v_mul_f32_e32 v111, v111, v151
	v_mul_f32_e32 v104, v104, v151
	v_mul_f32_e32 v105, v105, v151
	v_mul_f32_e32 v106, v106, v151
	v_mul_f32_e32 v107, v107, v151
	v_mul_f32_e32 v108, 0xbfb8aa3b, v108
	v_mul_f32_e32 v109, 0xbfb8aa3b, v109
	v_mul_f32_e32 v110, 0xbfb8aa3b, v110
	v_mul_f32_e32 v111, 0xbfb8aa3b, v111
	v_mul_f32_e32 v104, 0xbfb8aa3b, v104
	v_mul_f32_e32 v105, 0xbfb8aa3b, v105
	v_mul_f32_e32 v106, 0xbfb8aa3b, v106
	v_mul_f32_e32 v107, 0xbfb8aa3b, v107
	v_exp_f32_e32 v108, v108
	v_exp_f32_e32 v109, v109
	v_exp_f32_e32 v110, v110
	v_exp_f32_e32 v111, v111
	v_exp_f32_e32 v104, v104
	v_exp_f32_e32 v105, v105
	v_exp_f32_e32 v106, v106
	v_exp_f32_e32 v107, v107
	v_add_f32_e32 v108, 1.0, v108
	v_add_f32_e32 v109, 1.0, v109
	v_add_f32_e32 v110, 1.0, v110
	v_add_f32_e32 v111, 1.0, v111
	v_add_f32_e32 v104, 1.0, v104
	v_add_f32_e32 v105, 1.0, v105
	v_add_f32_e32 v106, 1.0, v106
	v_add_f32_e32 v107, 1.0, v107
	v_rcp_f32_e32 v108, v108
	v_rcp_f32_e32 v109, v109
	v_rcp_f32_e32 v110, v110
	v_rcp_f32_e32 v111, v111
	v_rcp_f32_e32 v104, v104
	v_rcp_f32_e32 v105, v105
	v_rcp_f32_e32 v106, v106
	v_rcp_f32_e32 v107, v107
	v_fma_f32 v108, v108, v170, v162
	v_fma_f32 v109, v109, v171, v163
	v_fma_f32 v110, v110, v172, v164
	v_fma_f32 v111, v111, v173, v165
	v_fma_f32 v104, v104, v174, v166
	v_fma_f32 v105, v105, v175, v167
	v_fma_f32 v106, v106, v180, v168
	v_fma_f32 v107, v107, v181, v169
	v_mul_f32_e32 v152, v109, v109
	v_mul_f32_e32 v153, v111, v111
	v_mul_f32_e32 v182, v105, v105
	v_mul_f32_e32 v183, v107, v107
	v_fmac_f32_e32 v152, v108, v108
	v_fmac_f32_e32 v153, v110, v110
	v_fmac_f32_e32 v182, v104, v104
	v_fmac_f32_e32 v183, v106, v106
	v_add_f32_e32 v152, v152, v153
	v_add_f32_e32 v182, v182, v183
	v_add_f32_e32 v224, v152, v182
	s_waitcnt lgkmcnt(0)
	v_add_f32_e32 v251, v251, v252
	ds_bpermute_b32 v252, v150, v251
	v_lshlrev_b32_e32 v162, 16, v208
	v_and_b32_e32 v163, 0xffff0000, v208
	v_lshlrev_b32_e32 v170, 16, v212
	v_and_b32_e32 v171, 0xffff0000, v212
	v_lshlrev_b32_e32 v164, 16, v209
	v_and_b32_e32 v165, 0xffff0000, v209
	v_lshlrev_b32_e32 v172, 16, v213
	v_and_b32_e32 v173, 0xffff0000, v213
	v_lshlrev_b32_e32 v166, 16, v210
	v_and_b32_e32 v167, 0xffff0000, v210
	v_lshlrev_b32_e32 v174, 16, v214
	v_and_b32_e32 v175, 0xffff0000, v214
	v_lshlrev_b32_e32 v168, 16, v211
	v_and_b32_e32 v169, 0xffff0000, v211
	v_lshlrev_b32_e32 v180, 16, v215
	v_and_b32_e32 v181, 0xffff0000, v215
	v_mul_f32_e32 v100, v100, v151
	v_mul_f32_e32 v101, v101, v151
	v_mul_f32_e32 v102, v102, v151
	v_mul_f32_e32 v103, v103, v151
	v_mul_f32_e32 v96, v96, v151
	v_mul_f32_e32 v97, v97, v151
	v_mul_f32_e32 v98, v98, v151
	v_mul_f32_e32 v99, v99, v151
	v_mul_f32_e32 v100, 0xbfb8aa3b, v100
	v_mul_f32_e32 v101, 0xbfb8aa3b, v101
	v_mul_f32_e32 v102, 0xbfb8aa3b, v102
	v_mul_f32_e32 v103, 0xbfb8aa3b, v103
	v_mul_f32_e32 v96, 0xbfb8aa3b, v96
	v_mul_f32_e32 v97, 0xbfb8aa3b, v97
	v_mul_f32_e32 v98, 0xbfb8aa3b, v98
	v_mul_f32_e32 v99, 0xbfb8aa3b, v99
	v_exp_f32_e32 v100, v100
	v_exp_f32_e32 v101, v101
	v_exp_f32_e32 v102, v102
	v_exp_f32_e32 v103, v103
	v_exp_f32_e32 v96, v96
	v_exp_f32_e32 v97, v97
	v_exp_f32_e32 v98, v98
	v_exp_f32_e32 v99, v99
	v_add_f32_e32 v100, 1.0, v100
	v_add_f32_e32 v101, 1.0, v101
	v_add_f32_e32 v102, 1.0, v102
	v_add_f32_e32 v103, 1.0, v103
	v_add_f32_e32 v96, 1.0, v96
	v_add_f32_e32 v97, 1.0, v97
	v_add_f32_e32 v98, 1.0, v98
	v_add_f32_e32 v99, 1.0, v99
	v_rcp_f32_e32 v100, v100
	v_rcp_f32_e32 v101, v101
	v_rcp_f32_e32 v102, v102
	v_rcp_f32_e32 v103, v103
	v_rcp_f32_e32 v96, v96
	v_rcp_f32_e32 v97, v97
	v_rcp_f32_e32 v98, v98
	v_rcp_f32_e32 v99, v99
	v_fma_f32 v100, v100, v170, v162
	v_fma_f32 v101, v101, v171, v163
	v_fma_f32 v102, v102, v172, v164
	v_fma_f32 v103, v103, v173, v165
	v_fma_f32 v96, v96, v174, v166
	v_fma_f32 v97, v97, v175, v167
	v_fma_f32 v98, v98, v180, v168
	v_fma_f32 v99, v99, v181, v169
	v_mul_f32_e32 v152, v101, v101
	v_mul_f32_e32 v153, v103, v103
	v_mul_f32_e32 v182, v97, v97
	v_mul_f32_e32 v183, v99, v99
	v_fmac_f32_e32 v152, v100, v100
	v_fmac_f32_e32 v153, v102, v102
	v_fmac_f32_e32 v182, v96, v96
	v_fmac_f32_e32 v183, v98, v98
	v_add_f32_e32 v152, v152, v153
	v_add_f32_e32 v182, v182, v183
	v_add_f32_e32 v250, v152, v182
	s_waitcnt lgkmcnt(0)
	v_add_f32_e32 v253, v251, v252
	s_and_saveexec_b64 s[44:45], s[6:7]
	global_atomic_add_f32 v148, v253, s[16:17] offset:0
	s_or_b64 exec, exec, s[44:45]
	s_add_u32 s48, s12, 0x90000
	s_addc_u32 s49, s13, 0
	s_add_u32 s50, s14, 0x90000
	s_addc_u32 s51, s15, 0
	global_load_dword v177, v148, s[22:23] offset:576
	global_load_dwordx4 v[200:203], v147, s[48:49] offset:0
	global_load_dwordx4 v[204:207], v147, s[50:51] offset:0
	global_load_dwordx4 v[208:211], v147, s[48:49] offset:256
	global_load_dwordx4 v[212:215], v147, s[50:51] offset:256
	v_add_f32_e32 v251, v224, v250
	ds_bpermute_b32 v252, v149, v251
	s_waitcnt vmcnt(16)
	v_fmamk_f32 v151, v178, 0x3a000000, v160
	v_mul_f32_e32 v152, 0x4b800000, v151
	v_cmp_gt_f32_e32 vcc, s65, v151
	s_nop 1
	v_cndmask_b32_e32 v151, v151, v152, vcc
	v_rsq_f32_e32 v151, v151
	s_nop 0
	v_mul_f32_e32 v152, 0x45800000, v151
	v_cndmask_b32_e32 v151, v151, v152, vcc
	v_lshlrev_b32_e32 v162, 16, v216
	v_and_b32_e32 v163, 0xffff0000, v216
	v_lshlrev_b32_e32 v170, 16, v220
	v_and_b32_e32 v171, 0xffff0000, v220
	v_lshlrev_b32_e32 v164, 16, v217
	v_and_b32_e32 v165, 0xffff0000, v217
	v_lshlrev_b32_e32 v172, 16, v221
	v_and_b32_e32 v173, 0xffff0000, v221
	v_lshlrev_b32_e32 v166, 16, v218
	v_and_b32_e32 v167, 0xffff0000, v218
	v_lshlrev_b32_e32 v174, 16, v222
	v_and_b32_e32 v175, 0xffff0000, v222
	v_lshlrev_b32_e32 v168, 16, v219
	v_and_b32_e32 v169, 0xffff0000, v219
	v_lshlrev_b32_e32 v180, 16, v223
	v_and_b32_e32 v181, 0xffff0000, v223
	v_mul_f32_e32 v92, v92, v151
	v_mul_f32_e32 v93, v93, v151
	v_mul_f32_e32 v94, v94, v151
	v_mul_f32_e32 v95, v95, v151
	v_mul_f32_e32 v88, v88, v151
	v_mul_f32_e32 v89, v89, v151
	v_mul_f32_e32 v90, v90, v151
	v_mul_f32_e32 v91, v91, v151
	v_mul_f32_e32 v92, 0xbfb8aa3b, v92
	v_mul_f32_e32 v93, 0xbfb8aa3b, v93
	v_mul_f32_e32 v94, 0xbfb8aa3b, v94
	v_mul_f32_e32 v95, 0xbfb8aa3b, v95
	v_mul_f32_e32 v88, 0xbfb8aa3b, v88
	v_mul_f32_e32 v89, 0xbfb8aa3b, v89
	v_mul_f32_e32 v90, 0xbfb8aa3b, v90
	v_mul_f32_e32 v91, 0xbfb8aa3b, v91
	v_exp_f32_e32 v92, v92
	v_exp_f32_e32 v93, v93
	v_exp_f32_e32 v94, v94
	v_exp_f32_e32 v95, v95
	v_exp_f32_e32 v88, v88
	v_exp_f32_e32 v89, v89
	v_exp_f32_e32 v90, v90
	v_exp_f32_e32 v91, v91
	v_add_f32_e32 v92, 1.0, v92
	v_add_f32_e32 v93, 1.0, v93
	v_add_f32_e32 v94, 1.0, v94
	v_add_f32_e32 v95, 1.0, v95
	v_add_f32_e32 v88, 1.0, v88
	v_add_f32_e32 v89, 1.0, v89
	v_add_f32_e32 v90, 1.0, v90
	v_add_f32_e32 v91, 1.0, v91
	v_rcp_f32_e32 v92, v92
	v_rcp_f32_e32 v93, v93
	v_rcp_f32_e32 v94, v94
	v_rcp_f32_e32 v95, v95
	v_rcp_f32_e32 v88, v88
	v_rcp_f32_e32 v89, v89
	v_rcp_f32_e32 v90, v90
	v_rcp_f32_e32 v91, v91
	v_fma_f32 v92, v92, v170, v162
	v_fma_f32 v93, v93, v171, v163
	v_fma_f32 v94, v94, v172, v164
	v_fma_f32 v95, v95, v173, v165
	v_fma_f32 v88, v88, v174, v166
	v_fma_f32 v89, v89, v175, v167
	v_fma_f32 v90, v90, v180, v168
	v_fma_f32 v91, v91, v181, v169
	v_mul_f32_e32 v152, v93, v93
	v_mul_f32_e32 v153, v95, v95
	v_mul_f32_e32 v182, v89, v89
	v_mul_f32_e32 v183, v91, v91
	v_fmac_f32_e32 v152, v92, v92
	v_fmac_f32_e32 v153, v94, v94
	v_fmac_f32_e32 v182, v88, v88
	v_fmac_f32_e32 v183, v90, v90
	v_add_f32_e32 v152, v152, v153
	v_add_f32_e32 v182, v182, v183
	v_add_f32_e32 v224, v152, v182
	s_waitcnt lgkmcnt(0)
	v_add_f32_e32 v251, v251, v252
	ds_bpermute_b32 v252, v150, v251
	v_lshlrev_b32_e32 v162, 16, v226
	v_and_b32_e32 v163, 0xffff0000, v226
	v_lshlrev_b32_e32 v170, 16, v230
	v_and_b32_e32 v171, 0xffff0000, v230
	v_lshlrev_b32_e32 v164, 16, v227
	v_and_b32_e32 v165, 0xffff0000, v227
	v_lshlrev_b32_e32 v172, 16, v231
	v_and_b32_e32 v173, 0xffff0000, v231
	v_lshlrev_b32_e32 v166, 16, v228
	v_and_b32_e32 v167, 0xffff0000, v228
	v_lshlrev_b32_e32 v174, 16, v232
	v_and_b32_e32 v175, 0xffff0000, v232
	v_lshlrev_b32_e32 v168, 16, v229
	v_and_b32_e32 v169, 0xffff0000, v229
	v_lshlrev_b32_e32 v180, 16, v233
	v_and_b32_e32 v181, 0xffff0000, v233
	v_mul_f32_e32 v84, v84, v151
	v_mul_f32_e32 v85, v85, v151
	v_mul_f32_e32 v86, v86, v151
	v_mul_f32_e32 v87, v87, v151
	v_mul_f32_e32 v80, v80, v151
	v_mul_f32_e32 v81, v81, v151
	v_mul_f32_e32 v82, v82, v151
	v_mul_f32_e32 v83, v83, v151
	v_mul_f32_e32 v84, 0xbfb8aa3b, v84
	v_mul_f32_e32 v85, 0xbfb8aa3b, v85
	v_mul_f32_e32 v86, 0xbfb8aa3b, v86
	v_mul_f32_e32 v87, 0xbfb8aa3b, v87
	v_mul_f32_e32 v80, 0xbfb8aa3b, v80
	v_mul_f32_e32 v81, 0xbfb8aa3b, v81
	v_mul_f32_e32 v82, 0xbfb8aa3b, v82
	v_mul_f32_e32 v83, 0xbfb8aa3b, v83
	v_exp_f32_e32 v84, v84
	v_exp_f32_e32 v85, v85
	v_exp_f32_e32 v86, v86
	v_exp_f32_e32 v87, v87
	v_exp_f32_e32 v80, v80
	v_exp_f32_e32 v81, v81
	v_exp_f32_e32 v82, v82
	v_exp_f32_e32 v83, v83
	v_add_f32_e32 v84, 1.0, v84
	v_add_f32_e32 v85, 1.0, v85
	v_add_f32_e32 v86, 1.0, v86
	v_add_f32_e32 v87, 1.0, v87
	v_add_f32_e32 v80, 1.0, v80
	v_add_f32_e32 v81, 1.0, v81
	v_add_f32_e32 v82, 1.0, v82
	v_add_f32_e32 v83, 1.0, v83
	v_rcp_f32_e32 v84, v84
	v_rcp_f32_e32 v85, v85
	v_rcp_f32_e32 v86, v86
	v_rcp_f32_e32 v87, v87
	v_rcp_f32_e32 v80, v80
	v_rcp_f32_e32 v81, v81
	v_rcp_f32_e32 v82, v82
	v_rcp_f32_e32 v83, v83
	v_fma_f32 v84, v84, v170, v162
	v_fma_f32 v85, v85, v171, v163
	v_fma_f32 v86, v86, v172, v164
	v_fma_f32 v87, v87, v173, v165
	v_fma_f32 v80, v80, v174, v166
	v_fma_f32 v81, v81, v175, v167
	v_fma_f32 v82, v82, v180, v168
	v_fma_f32 v83, v83, v181, v169
	v_mul_f32_e32 v152, v85, v85
	v_mul_f32_e32 v153, v87, v87
	v_mul_f32_e32 v182, v81, v81
	v_mul_f32_e32 v183, v83, v83
	v_fmac_f32_e32 v152, v84, v84
	v_fmac_f32_e32 v153, v86, v86
	v_fmac_f32_e32 v182, v80, v80
	v_fmac_f32_e32 v183, v82, v82
	v_add_f32_e32 v152, v152, v153
	v_add_f32_e32 v182, v182, v183
	v_add_f32_e32 v250, v152, v182
	s_waitcnt lgkmcnt(0)
	v_add_f32_e32 v253, v251, v252
	s_and_saveexec_b64 s[44:45], s[6:7]
	global_atomic_add_f32 v148, v253, s[16:17] offset:64
	s_or_b64 exec, exec, s[44:45]
	s_add_u32 s48, s12, 0xa0000
	s_addc_u32 s49, s13, 0
	s_add_u32 s50, s14, 0xa0000
	s_addc_u32 s51, s15, 0
	global_load_dword v178, v148, s[22:23] offset:640
	global_load_dwordx4 v[216:219], v147, s[48:49] offset:0
	global_load_dwordx4 v[220:223], v147, s[50:51] offset:0
	global_load_dwordx4 v[226:229], v147, s[48:49] offset:256
	global_load_dwordx4 v[230:233], v147, s[50:51] offset:256
	v_add_f32_e32 v251, v224, v250
	ds_bpermute_b32 v252, v149, v251
	s_waitcnt vmcnt(17)
	v_fmamk_f32 v151, v179, 0x3a000000, v160
	v_mul_f32_e32 v152, 0x4b800000, v151
	v_cmp_gt_f32_e32 vcc, s65, v151
	s_nop 1
	v_cndmask_b32_e32 v151, v151, v152, vcc
	v_rsq_f32_e32 v151, v151
	s_nop 0
	v_mul_f32_e32 v152, 0x45800000, v151
	v_cndmask_b32_e32 v151, v151, v152, vcc
	v_lshlrev_b32_e32 v162, 16, v234
	v_and_b32_e32 v163, 0xffff0000, v234
	v_lshlrev_b32_e32 v170, 16, v238
	v_and_b32_e32 v171, 0xffff0000, v238
	v_lshlrev_b32_e32 v164, 16, v235
	v_and_b32_e32 v165, 0xffff0000, v235
	v_lshlrev_b32_e32 v172, 16, v239
	v_and_b32_e32 v173, 0xffff0000, v239
	v_lshlrev_b32_e32 v166, 16, v236
	v_and_b32_e32 v167, 0xffff0000, v236
	v_lshlrev_b32_e32 v174, 16, v240
	v_and_b32_e32 v175, 0xffff0000, v240
	v_lshlrev_b32_e32 v168, 16, v237
	v_and_b32_e32 v169, 0xffff0000, v237
	v_lshlrev_b32_e32 v180, 16, v241
	v_and_b32_e32 v181, 0xffff0000, v241
	v_mul_f32_e32 v76, v76, v151
	v_mul_f32_e32 v77, v77, v151
	v_mul_f32_e32 v78, v78, v151
	v_mul_f32_e32 v79, v79, v151
	v_mul_f32_e32 v72, v72, v151
	v_mul_f32_e32 v73, v73, v151
	v_mul_f32_e32 v74, v74, v151
	v_mul_f32_e32 v75, v75, v151
	v_mul_f32_e32 v76, 0xbfb8aa3b, v76
	v_mul_f32_e32 v77, 0xbfb8aa3b, v77
	v_mul_f32_e32 v78, 0xbfb8aa3b, v78
	v_mul_f32_e32 v79, 0xbfb8aa3b, v79
	v_mul_f32_e32 v72, 0xbfb8aa3b, v72
	v_mul_f32_e32 v73, 0xbfb8aa3b, v73
	v_mul_f32_e32 v74, 0xbfb8aa3b, v74
	v_mul_f32_e32 v75, 0xbfb8aa3b, v75
	v_exp_f32_e32 v76, v76
	v_exp_f32_e32 v77, v77
	v_exp_f32_e32 v78, v78
	v_exp_f32_e32 v79, v79
	v_exp_f32_e32 v72, v72
	v_exp_f32_e32 v73, v73
	v_exp_f32_e32 v74, v74
	v_exp_f32_e32 v75, v75
	v_add_f32_e32 v76, 1.0, v76
	v_add_f32_e32 v77, 1.0, v77
	v_add_f32_e32 v78, 1.0, v78
	v_add_f32_e32 v79, 1.0, v79
	v_add_f32_e32 v72, 1.0, v72
	v_add_f32_e32 v73, 1.0, v73
	v_add_f32_e32 v74, 1.0, v74
	v_add_f32_e32 v75, 1.0, v75
	v_rcp_f32_e32 v76, v76
	v_rcp_f32_e32 v77, v77
	v_rcp_f32_e32 v78, v78
	v_rcp_f32_e32 v79, v79
	v_rcp_f32_e32 v72, v72
	v_rcp_f32_e32 v73, v73
	v_rcp_f32_e32 v74, v74
	v_rcp_f32_e32 v75, v75
	v_fma_f32 v76, v76, v170, v162
	v_fma_f32 v77, v77, v171, v163
	v_fma_f32 v78, v78, v172, v164
	v_fma_f32 v79, v79, v173, v165
	v_fma_f32 v72, v72, v174, v166
	v_fma_f32 v73, v73, v175, v167
	v_fma_f32 v74, v74, v180, v168
	v_fma_f32 v75, v75, v181, v169
	v_mul_f32_e32 v152, v77, v77
	v_mul_f32_e32 v153, v79, v79
	v_mul_f32_e32 v182, v73, v73
	v_mul_f32_e32 v183, v75, v75
	v_fmac_f32_e32 v152, v76, v76
	v_fmac_f32_e32 v153, v78, v78
	v_fmac_f32_e32 v182, v72, v72
	v_fmac_f32_e32 v183, v74, v74
	v_add_f32_e32 v152, v152, v153
	v_add_f32_e32 v182, v182, v183
	v_add_f32_e32 v224, v152, v182
	s_waitcnt lgkmcnt(0)
	v_add_f32_e32 v251, v251, v252
	ds_bpermute_b32 v252, v150, v251
	v_lshlrev_b32_e32 v162, 16, v242
	v_and_b32_e32 v163, 0xffff0000, v242
	v_lshlrev_b32_e32 v170, 16, v246
	v_and_b32_e32 v171, 0xffff0000, v246
	v_lshlrev_b32_e32 v164, 16, v243
	v_and_b32_e32 v165, 0xffff0000, v243
	v_lshlrev_b32_e32 v172, 16, v247
	v_and_b32_e32 v173, 0xffff0000, v247
	v_lshlrev_b32_e32 v166, 16, v244
	v_and_b32_e32 v167, 0xffff0000, v244
	v_lshlrev_b32_e32 v174, 16, v248
	v_and_b32_e32 v175, 0xffff0000, v248
	v_lshlrev_b32_e32 v168, 16, v245
	v_and_b32_e32 v169, 0xffff0000, v245
	v_lshlrev_b32_e32 v180, 16, v249
	v_and_b32_e32 v181, 0xffff0000, v249
	v_mul_f32_e32 v68, v68, v151
	v_mul_f32_e32 v69, v69, v151
	v_mul_f32_e32 v70, v70, v151
	v_mul_f32_e32 v71, v71, v151
	v_mul_f32_e32 v64, v64, v151
	v_mul_f32_e32 v65, v65, v151
	v_mul_f32_e32 v66, v66, v151
	v_mul_f32_e32 v67, v67, v151
	v_mul_f32_e32 v68, 0xbfb8aa3b, v68
	v_mul_f32_e32 v69, 0xbfb8aa3b, v69
	v_mul_f32_e32 v70, 0xbfb8aa3b, v70
	v_mul_f32_e32 v71, 0xbfb8aa3b, v71
	v_mul_f32_e32 v64, 0xbfb8aa3b, v64
	v_mul_f32_e32 v65, 0xbfb8aa3b, v65
	v_mul_f32_e32 v66, 0xbfb8aa3b, v66
	v_mul_f32_e32 v67, 0xbfb8aa3b, v67
	v_exp_f32_e32 v68, v68
	v_exp_f32_e32 v69, v69
	v_exp_f32_e32 v70, v70
	v_exp_f32_e32 v71, v71
	v_exp_f32_e32 v64, v64
	v_exp_f32_e32 v65, v65
	v_exp_f32_e32 v66, v66
	v_exp_f32_e32 v67, v67
	v_add_f32_e32 v68, 1.0, v68
	v_add_f32_e32 v69, 1.0, v69
	v_add_f32_e32 v70, 1.0, v70
	v_add_f32_e32 v71, 1.0, v71
	v_add_f32_e32 v64, 1.0, v64
	v_add_f32_e32 v65, 1.0, v65
	v_add_f32_e32 v66, 1.0, v66
	v_add_f32_e32 v67, 1.0, v67
	v_rcp_f32_e32 v68, v68
	v_rcp_f32_e32 v69, v69
	v_rcp_f32_e32 v70, v70
	v_rcp_f32_e32 v71, v71
	v_rcp_f32_e32 v64, v64
	v_rcp_f32_e32 v65, v65
	v_rcp_f32_e32 v66, v66
	v_rcp_f32_e32 v67, v67
	v_fma_f32 v68, v68, v170, v162
	v_fma_f32 v69, v69, v171, v163
	v_fma_f32 v70, v70, v172, v164
	v_fma_f32 v71, v71, v173, v165
	v_fma_f32 v64, v64, v174, v166
	v_fma_f32 v65, v65, v175, v167
	v_fma_f32 v66, v66, v180, v168
	v_fma_f32 v67, v67, v181, v169
	v_mul_f32_e32 v152, v69, v69
	v_mul_f32_e32 v153, v71, v71
	v_mul_f32_e32 v182, v65, v65
	v_mul_f32_e32 v183, v67, v67
	v_fmac_f32_e32 v152, v68, v68
	v_fmac_f32_e32 v153, v70, v70
	v_fmac_f32_e32 v182, v64, v64
	v_fmac_f32_e32 v183, v66, v66
	v_add_f32_e32 v152, v152, v153
	v_add_f32_e32 v182, v182, v183
	v_add_f32_e32 v250, v152, v182
	s_waitcnt lgkmcnt(0)
	v_add_f32_e32 v253, v251, v252
	s_and_saveexec_b64 s[44:45], s[6:7]
	global_atomic_add_f32 v148, v253, s[16:17] offset:128
	s_or_b64 exec, exec, s[44:45]
	s_add_u32 s48, s12, 0xb0000
	s_addc_u32 s49, s13, 0
	s_add_u32 s50, s14, 0xb0000
	s_addc_u32 s51, s15, 0
	global_load_dword v179, v148, s[22:23] offset:704
	global_load_dwordx4 v[234:237], v147, s[48:49] offset:0
	global_load_dwordx4 v[238:241], v147, s[50:51] offset:0
	global_load_dwordx4 v[242:245], v147, s[48:49] offset:256
	global_load_dwordx4 v[246:249], v147, s[50:51] offset:256
	v_add_f32_e32 v251, v224, v250
	ds_bpermute_b32 v252, v149, v251
	s_waitcnt vmcnt(18)
	v_fmamk_f32 v151, v176, 0x3a000000, v160
	v_mul_f32_e32 v152, 0x4b800000, v151
	v_cmp_gt_f32_e32 vcc, s65, v151
	s_nop 1
	v_cndmask_b32_e32 v151, v151, v152, vcc
	v_rsq_f32_e32 v151, v151
	s_nop 0
	v_mul_f32_e32 v152, 0x45800000, v151
	v_cndmask_b32_e32 v151, v151, v152, vcc
	v_lshlrev_b32_e32 v162, 16, v184
	v_and_b32_e32 v163, 0xffff0000, v184
	v_lshlrev_b32_e32 v170, 16, v188
	v_and_b32_e32 v171, 0xffff0000, v188
	v_lshlrev_b32_e32 v164, 16, v185
	v_and_b32_e32 v165, 0xffff0000, v185
	v_lshlrev_b32_e32 v172, 16, v189
	v_and_b32_e32 v173, 0xffff0000, v189
	v_lshlrev_b32_e32 v166, 16, v186
	v_and_b32_e32 v167, 0xffff0000, v186
	v_lshlrev_b32_e32 v174, 16, v190
	v_and_b32_e32 v175, 0xffff0000, v190
	v_lshlrev_b32_e32 v168, 16, v187
	v_and_b32_e32 v169, 0xffff0000, v187
	v_lshlrev_b32_e32 v180, 16, v191
	v_and_b32_e32 v181, 0xffff0000, v191
	v_mul_f32_e32 v60, v60, v151
	v_mul_f32_e32 v61, v61, v151
	v_mul_f32_e32 v62, v62, v151
	v_mul_f32_e32 v63, v63, v151
	v_mul_f32_e32 v56, v56, v151
	v_mul_f32_e32 v57, v57, v151
	v_mul_f32_e32 v58, v58, v151
	v_mul_f32_e32 v59, v59, v151
	v_mul_f32_e32 v60, 0xbfb8aa3b, v60
	v_mul_f32_e32 v61, 0xbfb8aa3b, v61
	v_mul_f32_e32 v62, 0xbfb8aa3b, v62
	v_mul_f32_e32 v63, 0xbfb8aa3b, v63
	v_mul_f32_e32 v56, 0xbfb8aa3b, v56
	v_mul_f32_e32 v57, 0xbfb8aa3b, v57
	v_mul_f32_e32 v58, 0xbfb8aa3b, v58
	v_mul_f32_e32 v59, 0xbfb8aa3b, v59
	v_exp_f32_e32 v60, v60
	v_exp_f32_e32 v61, v61
	v_exp_f32_e32 v62, v62
	v_exp_f32_e32 v63, v63
	v_exp_f32_e32 v56, v56
	v_exp_f32_e32 v57, v57
	v_exp_f32_e32 v58, v58
	v_exp_f32_e32 v59, v59
	v_add_f32_e32 v60, 1.0, v60
	v_add_f32_e32 v61, 1.0, v61
	v_add_f32_e32 v62, 1.0, v62
	v_add_f32_e32 v63, 1.0, v63
	v_add_f32_e32 v56, 1.0, v56
	v_add_f32_e32 v57, 1.0, v57
	v_add_f32_e32 v58, 1.0, v58
	v_add_f32_e32 v59, 1.0, v59
	v_rcp_f32_e32 v60, v60
	v_rcp_f32_e32 v61, v61
	v_rcp_f32_e32 v62, v62
	v_rcp_f32_e32 v63, v63
	v_rcp_f32_e32 v56, v56
	v_rcp_f32_e32 v57, v57
	v_rcp_f32_e32 v58, v58
	v_rcp_f32_e32 v59, v59
	v_fma_f32 v60, v60, v170, v162
	v_fma_f32 v61, v61, v171, v163
	v_fma_f32 v62, v62, v172, v164
	v_fma_f32 v63, v63, v173, v165
	v_fma_f32 v56, v56, v174, v166
	v_fma_f32 v57, v57, v175, v167
	v_fma_f32 v58, v58, v180, v168
	v_fma_f32 v59, v59, v181, v169
	v_mul_f32_e32 v152, v61, v61
	v_mul_f32_e32 v153, v63, v63
	v_mul_f32_e32 v182, v57, v57
	v_mul_f32_e32 v183, v59, v59
	v_fmac_f32_e32 v152, v60, v60
	v_fmac_f32_e32 v153, v62, v62
	v_fmac_f32_e32 v182, v56, v56
	v_fmac_f32_e32 v183, v58, v58
	v_add_f32_e32 v152, v152, v153
	v_add_f32_e32 v182, v182, v183
	v_add_f32_e32 v224, v152, v182
	s_waitcnt lgkmcnt(0)
	v_add_f32_e32 v251, v251, v252
	ds_bpermute_b32 v252, v150, v251
	v_lshlrev_b32_e32 v162, 16, v192
	v_and_b32_e32 v163, 0xffff0000, v192
	v_lshlrev_b32_e32 v170, 16, v196
	v_and_b32_e32 v171, 0xffff0000, v196
	v_lshlrev_b32_e32 v164, 16, v193
	v_and_b32_e32 v165, 0xffff0000, v193
	v_lshlrev_b32_e32 v172, 16, v197
	v_and_b32_e32 v173, 0xffff0000, v197
	v_lshlrev_b32_e32 v166, 16, v194
	v_and_b32_e32 v167, 0xffff0000, v194
	v_lshlrev_b32_e32 v174, 16, v198
	v_and_b32_e32 v175, 0xffff0000, v198
	v_lshlrev_b32_e32 v168, 16, v195
	v_and_b32_e32 v169, 0xffff0000, v195
	v_lshlrev_b32_e32 v180, 16, v199
	v_and_b32_e32 v181, 0xffff0000, v199
	v_mul_f32_e32 v52, v52, v151
	v_mul_f32_e32 v53, v53, v151
	v_mul_f32_e32 v54, v54, v151
	v_mul_f32_e32 v55, v55, v151
	v_mul_f32_e32 v48, v48, v151
	v_mul_f32_e32 v49, v49, v151
	v_mul_f32_e32 v50, v50, v151
	v_mul_f32_e32 v51, v51, v151
	v_mul_f32_e32 v52, 0xbfb8aa3b, v52
	v_mul_f32_e32 v53, 0xbfb8aa3b, v53
	v_mul_f32_e32 v54, 0xbfb8aa3b, v54
	v_mul_f32_e32 v55, 0xbfb8aa3b, v55
	v_mul_f32_e32 v48, 0xbfb8aa3b, v48
	v_mul_f32_e32 v49, 0xbfb8aa3b, v49
	v_mul_f32_e32 v50, 0xbfb8aa3b, v50
	v_mul_f32_e32 v51, 0xbfb8aa3b, v51
	v_exp_f32_e32 v52, v52
	v_exp_f32_e32 v53, v53
	v_exp_f32_e32 v54, v54
	v_exp_f32_e32 v55, v55
	v_exp_f32_e32 v48, v48
	v_exp_f32_e32 v49, v49
	v_exp_f32_e32 v50, v50
	v_exp_f32_e32 v51, v51
	v_add_f32_e32 v52, 1.0, v52
	v_add_f32_e32 v53, 1.0, v53
	v_add_f32_e32 v54, 1.0, v54
	v_add_f32_e32 v55, 1.0, v55
	v_add_f32_e32 v48, 1.0, v48
	v_add_f32_e32 v49, 1.0, v49
	v_add_f32_e32 v50, 1.0, v50
	v_add_f32_e32 v51, 1.0, v51
	v_rcp_f32_e32 v52, v52
	v_rcp_f32_e32 v53, v53
	v_rcp_f32_e32 v54, v54
	v_rcp_f32_e32 v55, v55
	v_rcp_f32_e32 v48, v48
	v_rcp_f32_e32 v49, v49
	v_rcp_f32_e32 v50, v50
	v_rcp_f32_e32 v51, v51
	v_fma_f32 v52, v52, v170, v162
	v_fma_f32 v53, v53, v171, v163
	v_fma_f32 v54, v54, v172, v164
	v_fma_f32 v55, v55, v173, v165
	v_fma_f32 v48, v48, v174, v166
	v_fma_f32 v49, v49, v175, v167
	v_fma_f32 v50, v50, v180, v168
	v_fma_f32 v51, v51, v181, v169
	v_mul_f32_e32 v152, v53, v53
	v_mul_f32_e32 v153, v55, v55
	v_mul_f32_e32 v182, v49, v49
	v_mul_f32_e32 v183, v51, v51
	v_fmac_f32_e32 v152, v52, v52
	v_fmac_f32_e32 v153, v54, v54
	v_fmac_f32_e32 v182, v48, v48
	v_fmac_f32_e32 v183, v50, v50
	v_add_f32_e32 v152, v152, v153
	v_add_f32_e32 v182, v182, v183
	v_add_f32_e32 v250, v152, v182
	s_waitcnt lgkmcnt(0)
	v_add_f32_e32 v253, v251, v252
	s_and_saveexec_b64 s[44:45], s[6:7]
	global_atomic_add_f32 v148, v253, s[16:17] offset:192
	s_or_b64 exec, exec, s[44:45]
	v_add_f32_e32 v251, v224, v250
	ds_bpermute_b32 v252, v149, v251
	s_waitcnt vmcnt(13)
	v_fmamk_f32 v151, v177, 0x3a000000, v160
	v_mul_f32_e32 v152, 0x4b800000, v151
	v_cmp_gt_f32_e32 vcc, s65, v151
	s_nop 1
	v_cndmask_b32_e32 v151, v151, v152, vcc
	v_rsq_f32_e32 v151, v151
	s_nop 0
	v_mul_f32_e32 v152, 0x45800000, v151
	v_cndmask_b32_e32 v151, v151, v152, vcc
	v_lshlrev_b32_e32 v162, 16, v200
	v_and_b32_e32 v163, 0xffff0000, v200
	v_lshlrev_b32_e32 v170, 16, v204
	v_and_b32_e32 v171, 0xffff0000, v204
	v_lshlrev_b32_e32 v164, 16, v201
	v_and_b32_e32 v165, 0xffff0000, v201
	v_lshlrev_b32_e32 v172, 16, v205
	v_and_b32_e32 v173, 0xffff0000, v205
	v_lshlrev_b32_e32 v166, 16, v202
	v_and_b32_e32 v167, 0xffff0000, v202
	v_lshlrev_b32_e32 v174, 16, v206
	v_and_b32_e32 v175, 0xffff0000, v206
	v_lshlrev_b32_e32 v168, 16, v203
	v_and_b32_e32 v169, 0xffff0000, v203
	v_lshlrev_b32_e32 v180, 16, v207
	v_and_b32_e32 v181, 0xffff0000, v207
	v_mul_f32_e32 v44, v44, v151
	v_mul_f32_e32 v45, v45, v151
	v_mul_f32_e32 v46, v46, v151
	v_mul_f32_e32 v47, v47, v151
	v_mul_f32_e32 v40, v40, v151
	v_mul_f32_e32 v41, v41, v151
	v_mul_f32_e32 v42, v42, v151
	v_mul_f32_e32 v43, v43, v151
	v_mul_f32_e32 v44, 0xbfb8aa3b, v44
	v_mul_f32_e32 v45, 0xbfb8aa3b, v45
	v_mul_f32_e32 v46, 0xbfb8aa3b, v46
	v_mul_f32_e32 v47, 0xbfb8aa3b, v47
	v_mul_f32_e32 v40, 0xbfb8aa3b, v40
	v_mul_f32_e32 v41, 0xbfb8aa3b, v41
	v_mul_f32_e32 v42, 0xbfb8aa3b, v42
	v_mul_f32_e32 v43, 0xbfb8aa3b, v43
	v_exp_f32_e32 v44, v44
	v_exp_f32_e32 v45, v45
	v_exp_f32_e32 v46, v46
	v_exp_f32_e32 v47, v47
	v_exp_f32_e32 v40, v40
	v_exp_f32_e32 v41, v41
	v_exp_f32_e32 v42, v42
	v_exp_f32_e32 v43, v43
	v_add_f32_e32 v44, 1.0, v44
	v_add_f32_e32 v45, 1.0, v45
	v_add_f32_e32 v46, 1.0, v46
	v_add_f32_e32 v47, 1.0, v47
	v_add_f32_e32 v40, 1.0, v40
	v_add_f32_e32 v41, 1.0, v41
	v_add_f32_e32 v42, 1.0, v42
	v_add_f32_e32 v43, 1.0, v43
	v_rcp_f32_e32 v44, v44
	v_rcp_f32_e32 v45, v45
	v_rcp_f32_e32 v46, v46
	v_rcp_f32_e32 v47, v47
	v_rcp_f32_e32 v40, v40
	v_rcp_f32_e32 v41, v41
	v_rcp_f32_e32 v42, v42
	v_rcp_f32_e32 v43, v43
	v_fma_f32 v44, v44, v170, v162
	v_fma_f32 v45, v45, v171, v163
	v_fma_f32 v46, v46, v172, v164
	v_fma_f32 v47, v47, v173, v165
	v_fma_f32 v40, v40, v174, v166
	v_fma_f32 v41, v41, v175, v167
	v_fma_f32 v42, v42, v180, v168
	v_fma_f32 v43, v43, v181, v169
	v_mul_f32_e32 v152, v45, v45
	v_mul_f32_e32 v153, v47, v47
	v_mul_f32_e32 v182, v41, v41
	v_mul_f32_e32 v183, v43, v43
	v_fmac_f32_e32 v152, v44, v44
	v_fmac_f32_e32 v153, v46, v46
	v_fmac_f32_e32 v182, v40, v40
	v_fmac_f32_e32 v183, v42, v42
	v_add_f32_e32 v152, v152, v153
	v_add_f32_e32 v182, v182, v183
	v_add_f32_e32 v224, v152, v182
	s_waitcnt lgkmcnt(0)
	v_add_f32_e32 v251, v251, v252
	ds_bpermute_b32 v252, v150, v251
	v_lshlrev_b32_e32 v162, 16, v208
	v_and_b32_e32 v163, 0xffff0000, v208
	v_lshlrev_b32_e32 v170, 16, v212
	v_and_b32_e32 v171, 0xffff0000, v212
	v_lshlrev_b32_e32 v164, 16, v209
	v_and_b32_e32 v165, 0xffff0000, v209
	v_lshlrev_b32_e32 v172, 16, v213
	v_and_b32_e32 v173, 0xffff0000, v213
	v_lshlrev_b32_e32 v166, 16, v210
	v_and_b32_e32 v167, 0xffff0000, v210
	v_lshlrev_b32_e32 v174, 16, v214
	v_and_b32_e32 v175, 0xffff0000, v214
	v_lshlrev_b32_e32 v168, 16, v211
	v_and_b32_e32 v169, 0xffff0000, v211
	v_lshlrev_b32_e32 v180, 16, v215
	v_and_b32_e32 v181, 0xffff0000, v215
	v_mul_f32_e32 v36, v36, v151
	v_mul_f32_e32 v37, v37, v151
	v_mul_f32_e32 v38, v38, v151
	v_mul_f32_e32 v39, v39, v151
	v_mul_f32_e32 v32, v32, v151
	v_mul_f32_e32 v33, v33, v151
	v_mul_f32_e32 v34, v34, v151
	v_mul_f32_e32 v35, v35, v151
	v_mul_f32_e32 v36, 0xbfb8aa3b, v36
	v_mul_f32_e32 v37, 0xbfb8aa3b, v37
	v_mul_f32_e32 v38, 0xbfb8aa3b, v38
	v_mul_f32_e32 v39, 0xbfb8aa3b, v39
	v_mul_f32_e32 v32, 0xbfb8aa3b, v32
	v_mul_f32_e32 v33, 0xbfb8aa3b, v33
	v_mul_f32_e32 v34, 0xbfb8aa3b, v34
	v_mul_f32_e32 v35, 0xbfb8aa3b, v35
	v_exp_f32_e32 v36, v36
	v_exp_f32_e32 v37, v37
	v_exp_f32_e32 v38, v38
	v_exp_f32_e32 v39, v39
	v_exp_f32_e32 v32, v32
	v_exp_f32_e32 v33, v33
	v_exp_f32_e32 v34, v34
	v_exp_f32_e32 v35, v35
	v_add_f32_e32 v36, 1.0, v36
	v_add_f32_e32 v37, 1.0, v37
	v_add_f32_e32 v38, 1.0, v38
	v_add_f32_e32 v39, 1.0, v39
	v_add_f32_e32 v32, 1.0, v32
	v_add_f32_e32 v33, 1.0, v33
	v_add_f32_e32 v34, 1.0, v34
	v_add_f32_e32 v35, 1.0, v35
	v_rcp_f32_e32 v36, v36
	v_rcp_f32_e32 v37, v37
	v_rcp_f32_e32 v38, v38
	v_rcp_f32_e32 v39, v39
	v_rcp_f32_e32 v32, v32
	v_rcp_f32_e32 v33, v33
	v_rcp_f32_e32 v34, v34
	v_rcp_f32_e32 v35, v35
	v_fma_f32 v36, v36, v170, v162
	v_fma_f32 v37, v37, v171, v163
	v_fma_f32 v38, v38, v172, v164
	v_fma_f32 v39, v39, v173, v165
	v_fma_f32 v32, v32, v174, v166
	v_fma_f32 v33, v33, v175, v167
	v_fma_f32 v34, v34, v180, v168
	v_fma_f32 v35, v35, v181, v169
	v_mul_f32_e32 v152, v37, v37
	v_mul_f32_e32 v153, v39, v39
	v_mul_f32_e32 v182, v33, v33
	v_mul_f32_e32 v183, v35, v35
	v_fmac_f32_e32 v152, v36, v36
	v_fmac_f32_e32 v153, v38, v38
	v_fmac_f32_e32 v182, v32, v32
	v_fmac_f32_e32 v183, v34, v34
	v_add_f32_e32 v152, v152, v153
	v_add_f32_e32 v182, v182, v183
	v_add_f32_e32 v250, v152, v182
	s_waitcnt lgkmcnt(0)
	v_add_f32_e32 v253, v251, v252
	s_and_saveexec_b64 s[44:45], s[6:7]
	global_atomic_add_f32 v148, v253, s[16:17] offset:512
	s_or_b64 exec, exec, s[44:45]
	v_add_f32_e32 v251, v224, v250
	ds_bpermute_b32 v252, v149, v251
	s_waitcnt vmcnt(8)
	v_fmamk_f32 v151, v178, 0x3a000000, v160
	v_mul_f32_e32 v152, 0x4b800000, v151
	v_cmp_gt_f32_e32 vcc, s65, v151
	s_nop 1
	v_cndmask_b32_e32 v151, v151, v152, vcc
	v_rsq_f32_e32 v151, v151
	s_nop 0
	v_mul_f32_e32 v152, 0x45800000, v151
	v_cndmask_b32_e32 v151, v151, v152, vcc
	v_lshlrev_b32_e32 v162, 16, v216
	v_and_b32_e32 v163, 0xffff0000, v216
	v_lshlrev_b32_e32 v170, 16, v220
	v_and_b32_e32 v171, 0xffff0000, v220
	v_lshlrev_b32_e32 v164, 16, v217
	v_and_b32_e32 v165, 0xffff0000, v217
	v_lshlrev_b32_e32 v172, 16, v221
	v_and_b32_e32 v173, 0xffff0000, v221
	v_lshlrev_b32_e32 v166, 16, v218
	v_and_b32_e32 v167, 0xffff0000, v218
	v_lshlrev_b32_e32 v174, 16, v222
	v_and_b32_e32 v175, 0xffff0000, v222
	v_lshlrev_b32_e32 v168, 16, v219
	v_and_b32_e32 v169, 0xffff0000, v219
	v_lshlrev_b32_e32 v180, 16, v223
	v_and_b32_e32 v181, 0xffff0000, v223
	v_mul_f32_e32 v28, v28, v151
	v_mul_f32_e32 v29, v29, v151
	v_mul_f32_e32 v30, v30, v151
	v_mul_f32_e32 v31, v31, v151
	v_mul_f32_e32 v24, v24, v151
	v_mul_f32_e32 v25, v25, v151
	v_mul_f32_e32 v26, v26, v151
	v_mul_f32_e32 v27, v27, v151
	v_mul_f32_e32 v28, 0xbfb8aa3b, v28
	v_mul_f32_e32 v29, 0xbfb8aa3b, v29
	v_mul_f32_e32 v30, 0xbfb8aa3b, v30
	v_mul_f32_e32 v31, 0xbfb8aa3b, v31
	v_mul_f32_e32 v24, 0xbfb8aa3b, v24
	v_mul_f32_e32 v25, 0xbfb8aa3b, v25
	v_mul_f32_e32 v26, 0xbfb8aa3b, v26
	v_mul_f32_e32 v27, 0xbfb8aa3b, v27
	v_exp_f32_e32 v28, v28
	v_exp_f32_e32 v29, v29
	v_exp_f32_e32 v30, v30
	v_exp_f32_e32 v31, v31
	v_exp_f32_e32 v24, v24
	v_exp_f32_e32 v25, v25
	v_exp_f32_e32 v26, v26
	v_exp_f32_e32 v27, v27
	v_add_f32_e32 v28, 1.0, v28
	v_add_f32_e32 v29, 1.0, v29
	v_add_f32_e32 v30, 1.0, v30
	v_add_f32_e32 v31, 1.0, v31
	v_add_f32_e32 v24, 1.0, v24
	v_add_f32_e32 v25, 1.0, v25
	v_add_f32_e32 v26, 1.0, v26
	v_add_f32_e32 v27, 1.0, v27
	v_rcp_f32_e32 v28, v28
	v_rcp_f32_e32 v29, v29
	v_rcp_f32_e32 v30, v30
	v_rcp_f32_e32 v31, v31
	v_rcp_f32_e32 v24, v24
	v_rcp_f32_e32 v25, v25
	v_rcp_f32_e32 v26, v26
	v_rcp_f32_e32 v27, v27
	v_fma_f32 v28, v28, v170, v162
	v_fma_f32 v29, v29, v171, v163
	v_fma_f32 v30, v30, v172, v164
	v_fma_f32 v31, v31, v173, v165
	v_fma_f32 v24, v24, v174, v166
	v_fma_f32 v25, v25, v175, v167
	v_fma_f32 v26, v26, v180, v168
	v_fma_f32 v27, v27, v181, v169
	v_mul_f32_e32 v152, v29, v29
	v_mul_f32_e32 v153, v31, v31
	v_mul_f32_e32 v182, v25, v25
	v_mul_f32_e32 v183, v27, v27
	v_fmac_f32_e32 v152, v28, v28
	v_fmac_f32_e32 v153, v30, v30
	v_fmac_f32_e32 v182, v24, v24
	v_fmac_f32_e32 v183, v26, v26
	v_add_f32_e32 v152, v152, v153
	v_add_f32_e32 v182, v182, v183
	v_add_f32_e32 v224, v152, v182
	s_waitcnt lgkmcnt(0)
	v_add_f32_e32 v251, v251, v252
	ds_bpermute_b32 v252, v150, v251
	v_lshlrev_b32_e32 v162, 16, v226
	v_and_b32_e32 v163, 0xffff0000, v226
	v_lshlrev_b32_e32 v170, 16, v230
	v_and_b32_e32 v171, 0xffff0000, v230
	v_lshlrev_b32_e32 v164, 16, v227
	v_and_b32_e32 v165, 0xffff0000, v227
	v_lshlrev_b32_e32 v172, 16, v231
	v_and_b32_e32 v173, 0xffff0000, v231
	v_lshlrev_b32_e32 v166, 16, v228
	v_and_b32_e32 v167, 0xffff0000, v228
	v_lshlrev_b32_e32 v174, 16, v232
	v_and_b32_e32 v175, 0xffff0000, v232
	v_lshlrev_b32_e32 v168, 16, v229
	v_and_b32_e32 v169, 0xffff0000, v229
	v_lshlrev_b32_e32 v180, 16, v233
	v_and_b32_e32 v181, 0xffff0000, v233
	v_mul_f32_e32 v20, v20, v151
	v_mul_f32_e32 v21, v21, v151
	v_mul_f32_e32 v22, v22, v151
	v_mul_f32_e32 v23, v23, v151
	v_mul_f32_e32 v16, v16, v151
	v_mul_f32_e32 v17, v17, v151
	v_mul_f32_e32 v18, v18, v151
	v_mul_f32_e32 v19, v19, v151
	v_mul_f32_e32 v20, 0xbfb8aa3b, v20
	v_mul_f32_e32 v21, 0xbfb8aa3b, v21
	v_mul_f32_e32 v22, 0xbfb8aa3b, v22
	v_mul_f32_e32 v23, 0xbfb8aa3b, v23
	v_mul_f32_e32 v16, 0xbfb8aa3b, v16
	v_mul_f32_e32 v17, 0xbfb8aa3b, v17
	v_mul_f32_e32 v18, 0xbfb8aa3b, v18
	v_mul_f32_e32 v19, 0xbfb8aa3b, v19
	v_exp_f32_e32 v20, v20
	v_exp_f32_e32 v21, v21
	v_exp_f32_e32 v22, v22
	v_exp_f32_e32 v23, v23
	v_exp_f32_e32 v16, v16
	v_exp_f32_e32 v17, v17
	v_exp_f32_e32 v18, v18
	v_exp_f32_e32 v19, v19
	v_add_f32_e32 v20, 1.0, v20
	v_add_f32_e32 v21, 1.0, v21
	v_add_f32_e32 v22, 1.0, v22
	v_add_f32_e32 v23, 1.0, v23
	v_add_f32_e32 v16, 1.0, v16
	v_add_f32_e32 v17, 1.0, v17
	v_add_f32_e32 v18, 1.0, v18
	v_add_f32_e32 v19, 1.0, v19
	v_rcp_f32_e32 v20, v20
	v_rcp_f32_e32 v21, v21
	v_rcp_f32_e32 v22, v22
	v_rcp_f32_e32 v23, v23
	v_rcp_f32_e32 v16, v16
	v_rcp_f32_e32 v17, v17
	v_rcp_f32_e32 v18, v18
	v_rcp_f32_e32 v19, v19
	v_fma_f32 v20, v20, v170, v162
	v_fma_f32 v21, v21, v171, v163
	v_fma_f32 v22, v22, v172, v164
	v_fma_f32 v23, v23, v173, v165
	v_fma_f32 v16, v16, v174, v166
	v_fma_f32 v17, v17, v175, v167
	v_fma_f32 v18, v18, v180, v168
	v_fma_f32 v19, v19, v181, v169
	v_mul_f32_e32 v152, v21, v21
	v_mul_f32_e32 v153, v23, v23
	v_mul_f32_e32 v182, v17, v17
	v_mul_f32_e32 v183, v19, v19
	v_fmac_f32_e32 v152, v20, v20
	v_fmac_f32_e32 v153, v22, v22
	v_fmac_f32_e32 v182, v16, v16
	v_fmac_f32_e32 v183, v18, v18
	v_add_f32_e32 v152, v152, v153
	v_add_f32_e32 v182, v182, v183
	v_add_f32_e32 v250, v152, v182
	s_waitcnt lgkmcnt(0)
	v_add_f32_e32 v253, v251, v252
	s_and_saveexec_b64 s[44:45], s[6:7]
	global_atomic_add_f32 v148, v253, s[16:17] offset:576
	s_or_b64 exec, exec, s[44:45]
	v_add_f32_e32 v251, v224, v250
	ds_bpermute_b32 v252, v149, v251
	s_waitcnt vmcnt(3)
	v_fmamk_f32 v151, v179, 0x3a000000, v160
	v_mul_f32_e32 v152, 0x4b800000, v151
	v_cmp_gt_f32_e32 vcc, s65, v151
	s_nop 1
	v_cndmask_b32_e32 v151, v151, v152, vcc
	v_rsq_f32_e32 v151, v151
	s_nop 0
	v_mul_f32_e32 v152, 0x45800000, v151
	v_cndmask_b32_e32 v151, v151, v152, vcc
	v_lshlrev_b32_e32 v162, 16, v234
	v_and_b32_e32 v163, 0xffff0000, v234
	v_lshlrev_b32_e32 v170, 16, v238
	v_and_b32_e32 v171, 0xffff0000, v238
	v_lshlrev_b32_e32 v164, 16, v235
	v_and_b32_e32 v165, 0xffff0000, v235
	v_lshlrev_b32_e32 v172, 16, v239
	v_and_b32_e32 v173, 0xffff0000, v239
	v_lshlrev_b32_e32 v166, 16, v236
	v_and_b32_e32 v167, 0xffff0000, v236
	v_lshlrev_b32_e32 v174, 16, v240
	v_and_b32_e32 v175, 0xffff0000, v240
	v_lshlrev_b32_e32 v168, 16, v237
	v_and_b32_e32 v169, 0xffff0000, v237
	v_lshlrev_b32_e32 v180, 16, v241
	v_and_b32_e32 v181, 0xffff0000, v241
	v_mul_f32_e32 v12, v12, v151
	v_mul_f32_e32 v13, v13, v151
	v_mul_f32_e32 v14, v14, v151
	v_mul_f32_e32 v15, v15, v151
	v_mul_f32_e32 v8, v8, v151
	v_mul_f32_e32 v9, v9, v151
	v_mul_f32_e32 v10, v10, v151
	v_mul_f32_e32 v11, v11, v151
	v_mul_f32_e32 v12, 0xbfb8aa3b, v12
	v_mul_f32_e32 v13, 0xbfb8aa3b, v13
	v_mul_f32_e32 v14, 0xbfb8aa3b, v14
	v_mul_f32_e32 v15, 0xbfb8aa3b, v15
	v_mul_f32_e32 v8, 0xbfb8aa3b, v8
	v_mul_f32_e32 v9, 0xbfb8aa3b, v9
	v_mul_f32_e32 v10, 0xbfb8aa3b, v10
	v_mul_f32_e32 v11, 0xbfb8aa3b, v11
	v_exp_f32_e32 v12, v12
	v_exp_f32_e32 v13, v13
	v_exp_f32_e32 v14, v14
	v_exp_f32_e32 v15, v15
	v_exp_f32_e32 v8, v8
	v_exp_f32_e32 v9, v9
	v_exp_f32_e32 v10, v10
	v_exp_f32_e32 v11, v11
	v_add_f32_e32 v12, 1.0, v12
	v_add_f32_e32 v13, 1.0, v13
	v_add_f32_e32 v14, 1.0, v14
	v_add_f32_e32 v15, 1.0, v15
	v_add_f32_e32 v8, 1.0, v8
	v_add_f32_e32 v9, 1.0, v9
	v_add_f32_e32 v10, 1.0, v10
	v_add_f32_e32 v11, 1.0, v11
	v_rcp_f32_e32 v12, v12
	v_rcp_f32_e32 v13, v13
	v_rcp_f32_e32 v14, v14
	v_rcp_f32_e32 v15, v15
	v_rcp_f32_e32 v8, v8
	v_rcp_f32_e32 v9, v9
	v_rcp_f32_e32 v10, v10
	v_rcp_f32_e32 v11, v11
	v_fma_f32 v12, v12, v170, v162
	v_fma_f32 v13, v13, v171, v163
	v_fma_f32 v14, v14, v172, v164
	v_fma_f32 v15, v15, v173, v165
	v_fma_f32 v8, v8, v174, v166
	v_fma_f32 v9, v9, v175, v167
	v_fma_f32 v10, v10, v180, v168
	v_fma_f32 v11, v11, v181, v169
	v_mul_f32_e32 v152, v13, v13
	v_mul_f32_e32 v153, v15, v15
	v_mul_f32_e32 v182, v9, v9
	v_mul_f32_e32 v183, v11, v11
	v_fmac_f32_e32 v152, v12, v12
	v_fmac_f32_e32 v153, v14, v14
	v_fmac_f32_e32 v182, v8, v8
	v_fmac_f32_e32 v183, v10, v10
	v_add_f32_e32 v152, v152, v153
	v_add_f32_e32 v182, v182, v183
	v_add_f32_e32 v224, v152, v182
	s_waitcnt lgkmcnt(0)
	v_add_f32_e32 v251, v251, v252
	ds_bpermute_b32 v252, v150, v251
	v_lshlrev_b32_e32 v162, 16, v242
	v_and_b32_e32 v163, 0xffff0000, v242
	v_lshlrev_b32_e32 v170, 16, v246
	v_and_b32_e32 v171, 0xffff0000, v246
	v_lshlrev_b32_e32 v164, 16, v243
	v_and_b32_e32 v165, 0xffff0000, v243
	v_lshlrev_b32_e32 v172, 16, v247
	v_and_b32_e32 v173, 0xffff0000, v247
	v_lshlrev_b32_e32 v166, 16, v244
	v_and_b32_e32 v167, 0xffff0000, v244
	v_lshlrev_b32_e32 v174, 16, v248
	v_and_b32_e32 v175, 0xffff0000, v248
	v_lshlrev_b32_e32 v168, 16, v245
	v_and_b32_e32 v169, 0xffff0000, v245
	v_lshlrev_b32_e32 v180, 16, v249
	v_and_b32_e32 v181, 0xffff0000, v249
	v_mul_f32_e32 v4, v4, v151
	v_mul_f32_e32 v5, v5, v151
	v_mul_f32_e32 v6, v6, v151
	v_mul_f32_e32 v7, v7, v151
	v_mul_f32_e32 v0, v0, v151
	v_mul_f32_e32 v1, v1, v151
	v_mul_f32_e32 v2, v2, v151
	v_mul_f32_e32 v3, v3, v151
	v_mul_f32_e32 v4, 0xbfb8aa3b, v4
	v_mul_f32_e32 v5, 0xbfb8aa3b, v5
	v_mul_f32_e32 v6, 0xbfb8aa3b, v6
	v_mul_f32_e32 v7, 0xbfb8aa3b, v7
	v_mul_f32_e32 v0, 0xbfb8aa3b, v0
	v_mul_f32_e32 v1, 0xbfb8aa3b, v1
	v_mul_f32_e32 v2, 0xbfb8aa3b, v2
	v_mul_f32_e32 v3, 0xbfb8aa3b, v3
	v_exp_f32_e32 v4, v4
	v_exp_f32_e32 v5, v5
	v_exp_f32_e32 v6, v6
	v_exp_f32_e32 v7, v7
	v_exp_f32_e32 v0, v0
	v_exp_f32_e32 v1, v1
	v_exp_f32_e32 v2, v2
	v_exp_f32_e32 v3, v3
	v_add_f32_e32 v4, 1.0, v4
	v_add_f32_e32 v5, 1.0, v5
	v_add_f32_e32 v6, 1.0, v6
	v_add_f32_e32 v7, 1.0, v7
	v_add_f32_e32 v0, 1.0, v0
	v_add_f32_e32 v1, 1.0, v1
	v_add_f32_e32 v2, 1.0, v2
	v_add_f32_e32 v3, 1.0, v3
	v_rcp_f32_e32 v4, v4
	v_rcp_f32_e32 v5, v5
	v_rcp_f32_e32 v6, v6
	v_rcp_f32_e32 v7, v7
	v_rcp_f32_e32 v0, v0
	v_rcp_f32_e32 v1, v1
	v_rcp_f32_e32 v2, v2
	v_rcp_f32_e32 v3, v3
	v_fma_f32 v4, v4, v170, v162
	v_fma_f32 v5, v5, v171, v163
	v_fma_f32 v6, v6, v172, v164
	v_fma_f32 v7, v7, v173, v165
	v_fma_f32 v0, v0, v174, v166
	v_fma_f32 v1, v1, v175, v167
	v_fma_f32 v2, v2, v180, v168
	v_fma_f32 v3, v3, v181, v169
	v_mul_f32_e32 v152, v5, v5
	v_mul_f32_e32 v153, v7, v7
	v_mul_f32_e32 v182, v1, v1
	v_mul_f32_e32 v183, v3, v3
	v_fmac_f32_e32 v152, v4, v4
	v_fmac_f32_e32 v153, v6, v6
	v_fmac_f32_e32 v182, v0, v0
	v_fmac_f32_e32 v183, v2, v2
	v_add_f32_e32 v152, v152, v153
	v_add_f32_e32 v182, v182, v183
	v_add_f32_e32 v250, v152, v182
	s_waitcnt lgkmcnt(0)
	v_add_f32_e32 v253, v251, v252
	s_and_saveexec_b64 s[44:45], s[6:7]
	global_atomic_add_f32 v148, v253, s[16:17] offset:640
	s_or_b64 exec, exec, s[44:45]
	v_add_f32_e32 v251, v224, v250
	ds_bpermute_b32 v252, v149, v251
	s_waitcnt lgkmcnt(0)
	v_add_f32_e32 v251, v251, v252
	ds_bpermute_b32 v252, v150, v251
	s_waitcnt lgkmcnt(0)
	v_add_f32_e32 v253, v251, v252
	s_and_saveexec_b64 s[44:45], s[6:7]
	global_atomic_add_f32 v148, v253, s[16:17] offset:704
	s_or_b64 exec, exec, s[44:45]
	v_lshlrev_b32_e32 v152, 2, v144
	global_load_dwordx4 v[200:203], v152, s[18:19] offset:0
	global_load_dwordx4 v[204:207], v152, s[18:19] offset:16
	global_load_dwordx4 v[208:211], v152, s[18:19] offset:512
	global_load_dwordx4 v[212:215], v152, s[18:19] offset:528
	s_waitcnt vmcnt(0)
	s_barrier
	s_add_i32 s99, s99, 1
	s_lshl_b32 s86, s99, 3
	v_readfirstlane_b32 s87, v225
	s_nop 3
	s_cmp_lt_u32 s87, 64
	s_cbranch_scc0 .Lp4_gs_join
	s_mov_b64 s[92:93], exec
	s_mov_b64 exec, 1
	v_mov_b32_e32 v192, 0
	v_mov_b32_e32 v193, 1
	global_atomic_add v192, v193, s[88:89]
	s_mov_b32 s90, 0

.Lp4_gs_join:
	s_barrier
	global_load_dword v184, v148, s[16:17] offset:0 sc1
	global_load_dword v185, v148, s[16:17] offset:64 sc1
	global_load_dword v186, v148, s[16:17] offset:128 sc1
	global_load_dword v187, v148, s[16:17] offset:192 sc1
	global_load_dword v188, v148, s[16:17] offset:512 sc1
	global_load_dword v189, v148, s[16:17] offset:576 sc1
	global_load_dword v190, v148, s[16:17] offset:640 sc1
	global_load_dword v191, v148, s[16:17] offset:704 sc1
	v_lshlrev_b32_e32 v147, 2, v145
	s_waitcnt vmcnt(7)
	v_fmamk_f32 v151, v184, 0x3a000000, v160
	v_mul_f32_e32 v152, 0x4b800000, v151
	v_cmp_gt_f32_e32 vcc, s65, v151
	s_nop 1
	v_cndmask_b32_e32 v151, v151, v152, vcc
	v_rsq_f32_e32 v151, v151
	s_nop 0
	v_mul_f32_e32 v152, 0x45800000, v151
	v_cndmask_b32_e32 v151, v151, v152, vcc
	s_mov_b64 s[52:53], s[20:21]
	v_mul_f32_e32 v124, v151, v124
	v_mul_f32_e32 v125, v151, v125
	v_mul_f32_e32 v126, v151, v126
	v_mul_f32_e32 v127, v151, v127
	v_mul_f32_e32 v120, v151, v120
	v_mul_f32_e32 v121, v151, v121
	v_mul_f32_e32 v122, v151, v122
	v_mul_f32_e32 v123, v151, v123
	v_mul_f32_e32 v124, v200, v124
	v_mul_f32_e32 v125, v201, v125
	v_mul_f32_e32 v126, v202, v126
	v_mul_f32_e32 v127, v203, v127
	v_mul_f32_e32 v120, v204, v120
	v_mul_f32_e32 v121, v205, v121
	v_mul_f32_e32 v122, v206, v122
	v_mul_f32_e32 v123, v207, v123
	global_store_dwordx4 v147, v[124:127], s[52:53] offset:0
	global_store_dwordx4 v147, v[120:123], s[52:53] offset:16
	v_mul_f32_e32 v116, v151, v116
	v_mul_f32_e32 v117, v151, v117
	v_mul_f32_e32 v118, v151, v118
	v_mul_f32_e32 v119, v151, v119
	v_mul_f32_e32 v112, v151, v112
	v_mul_f32_e32 v113, v151, v113
	v_mul_f32_e32 v114, v151, v114
	v_mul_f32_e32 v115, v151, v115
	v_mul_f32_e32 v116, v208, v116
	v_mul_f32_e32 v117, v209, v117
	v_mul_f32_e32 v118, v210, v118
	v_mul_f32_e32 v119, v211, v119
	v_mul_f32_e32 v112, v212, v112
	v_mul_f32_e32 v113, v213, v113
	v_mul_f32_e32 v114, v214, v114
	v_mul_f32_e32 v115, v215, v115
	global_store_dwordx4 v147, v[116:119], s[52:53] offset:512
	global_store_dwordx4 v147, v[112:115], s[52:53] offset:528
	s_waitcnt vmcnt(10)
	v_fmamk_f32 v151, v185, 0x3a000000, v160
	v_mul_f32_e32 v152, 0x4b800000, v151
	v_cmp_gt_f32_e32 vcc, s65, v151
	s_nop 1
	v_cndmask_b32_e32 v151, v151, v152, vcc
	v_rsq_f32_e32 v151, v151
	s_nop 0
	v_mul_f32_e32 v152, 0x45800000, v151
	v_cndmask_b32_e32 v151, v151, v152, vcc
	s_add_u32 s52, s20, 0x20000
	s_addc_u32 s53, s21, 0
	v_mul_f32_e32 v108, v151, v108
	v_mul_f32_e32 v109, v151, v109
	v_mul_f32_e32 v110, v151, v110
	v_mul_f32_e32 v111, v151, v111
	v_mul_f32_e32 v104, v151, v104
	v_mul_f32_e32 v105, v151, v105
	v_mul_f32_e32 v106, v151, v106
	v_mul_f32_e32 v107, v151, v107
	v_mul_f32_e32 v108, v200, v108
	v_mul_f32_e32 v109, v201, v109
	v_mul_f32_e32 v110, v202, v110
	v_mul_f32_e32 v111, v203, v111
	v_mul_f32_e32 v104, v204, v104
	v_mul_f32_e32 v105, v205, v105
	v_mul_f32_e32 v106, v206, v106
	v_mul_f32_e32 v107, v207, v107
	global_store_dwordx4 v147, v[108:111], s[52:53] offset:0
	global_store_dwordx4 v147, v[104:107], s[52:53] offset:16
	v_mul_f32_e32 v100, v151, v100
	v_mul_f32_e32 v101, v151, v101
	v_mul_f32_e32 v102, v151, v102
	v_mul_f32_e32 v103, v151, v103
	v_mul_f32_e32 v96, v151, v96
	v_mul_f32_e32 v97, v151, v97
	v_mul_f32_e32 v98, v151, v98
	v_mul_f32_e32 v99, v151, v99
	v_mul_f32_e32 v100, v208, v100
	v_mul_f32_e32 v101, v209, v101
	v_mul_f32_e32 v102, v210, v102
	v_mul_f32_e32 v103, v211, v103
	v_mul_f32_e32 v96, v212, v96
	v_mul_f32_e32 v97, v213, v97
	v_mul_f32_e32 v98, v214, v98
	v_mul_f32_e32 v99, v215, v99
	global_store_dwordx4 v147, v[100:103], s[52:53] offset:512
	global_store_dwordx4 v147, v[96:99], s[52:53] offset:528
	s_waitcnt vmcnt(13)
	v_fmamk_f32 v151, v186, 0x3a000000, v160
	v_mul_f32_e32 v152, 0x4b800000, v151
	v_cmp_gt_f32_e32 vcc, s65, v151
	s_nop 1
	v_cndmask_b32_e32 v151, v151, v152, vcc
	v_rsq_f32_e32 v151, v151
	s_nop 0
	v_mul_f32_e32 v152, 0x45800000, v151
	v_cndmask_b32_e32 v151, v151, v152, vcc
	s_add_u32 s52, s20, 0x40000
	s_addc_u32 s53, s21, 0
	v_mul_f32_e32 v92, v151, v92
	v_mul_f32_e32 v93, v151, v93
	v_mul_f32_e32 v94, v151, v94
	v_mul_f32_e32 v95, v151, v95
	v_mul_f32_e32 v88, v151, v88
	v_mul_f32_e32 v89, v151, v89
	v_mul_f32_e32 v90, v151, v90
	v_mul_f32_e32 v91, v151, v91
	v_mul_f32_e32 v92, v200, v92
	v_mul_f32_e32 v93, v201, v93
	v_mul_f32_e32 v94, v202, v94
	v_mul_f32_e32 v95, v203, v95
	v_mul_f32_e32 v88, v204, v88
	v_mul_f32_e32 v89, v205, v89
	v_mul_f32_e32 v90, v206, v90
	v_mul_f32_e32 v91, v207, v91
	global_store_dwordx4 v147, v[92:95], s[52:53] offset:0
	global_store_dwordx4 v147, v[88:91], s[52:53] offset:16
	v_mul_f32_e32 v84, v151, v84
	v_mul_f32_e32 v85, v151, v85
	v_mul_f32_e32 v86, v151, v86
	v_mul_f32_e32 v87, v151, v87
	v_mul_f32_e32 v80, v151, v80
	v_mul_f32_e32 v81, v151, v81
	v_mul_f32_e32 v82, v151, v82
	v_mul_f32_e32 v83, v151, v83
	v_mul_f32_e32 v84, v208, v84
	v_mul_f32_e32 v85, v209, v85
	v_mul_f32_e32 v86, v210, v86
	v_mul_f32_e32 v87, v211, v87
	v_mul_f32_e32 v80, v212, v80
	v_mul_f32_e32 v81, v213, v81
	v_mul_f32_e32 v82, v214, v82
	v_mul_f32_e32 v83, v215, v83
	global_store_dwordx4 v147, v[84:87], s[52:53] offset:512
	global_store_dwordx4 v147, v[80:83], s[52:53] offset:528
	s_waitcnt vmcnt(16)
	v_fmamk_f32 v151, v187, 0x3a000000, v160
	v_mul_f32_e32 v152, 0x4b800000, v151
	v_cmp_gt_f32_e32 vcc, s65, v151
	s_nop 1
	v_cndmask_b32_e32 v151, v151, v152, vcc
	v_rsq_f32_e32 v151, v151
	s_nop 0
	v_mul_f32_e32 v152, 0x45800000, v151
	v_cndmask_b32_e32 v151, v151, v152, vcc
	s_add_u32 s52, s20, 0x60000
	s_addc_u32 s53, s21, 0
	v_mul_f32_e32 v76, v151, v76
	v_mul_f32_e32 v77, v151, v77
	v_mul_f32_e32 v78, v151, v78
	v_mul_f32_e32 v79, v151, v79
	v_mul_f32_e32 v72, v151, v72
	v_mul_f32_e32 v73, v151, v73
	v_mul_f32_e32 v74, v151, v74
	v_mul_f32_e32 v75, v151, v75
	v_mul_f32_e32 v76, v200, v76
	v_mul_f32_e32 v77, v201, v77
	v_mul_f32_e32 v78, v202, v78
	v_mul_f32_e32 v79, v203, v79
	v_mul_f32_e32 v72, v204, v72
	v_mul_f32_e32 v73, v205, v73
	v_mul_f32_e32 v74, v206, v74
	v_mul_f32_e32 v75, v207, v75
	global_store_dwordx4 v147, v[76:79], s[52:53] offset:0
	global_store_dwordx4 v147, v[72:75], s[52:53] offset:16
	v_mul_f32_e32 v68, v151, v68
	v_mul_f32_e32 v69, v151, v69
	v_mul_f32_e32 v70, v151, v70
	v_mul_f32_e32 v71, v151, v71
	v_mul_f32_e32 v64, v151, v64
	v_mul_f32_e32 v65, v151, v65
	v_mul_f32_e32 v66, v151, v66
	v_mul_f32_e32 v67, v151, v67
	v_mul_f32_e32 v68, v208, v68
	v_mul_f32_e32 v69, v209, v69
	v_mul_f32_e32 v70, v210, v70
	v_mul_f32_e32 v71, v211, v71
	v_mul_f32_e32 v64, v212, v64
	v_mul_f32_e32 v65, v213, v65
	v_mul_f32_e32 v66, v214, v66
	v_mul_f32_e32 v67, v215, v67
	global_store_dwordx4 v147, v[68:71], s[52:53] offset:512
	global_store_dwordx4 v147, v[64:67], s[52:53] offset:528
	s_waitcnt vmcnt(19)
	v_fmamk_f32 v151, v188, 0x3a000000, v160
	v_mul_f32_e32 v152, 0x4b800000, v151
	v_cmp_gt_f32_e32 vcc, s65, v151
	s_nop 1
	v_cndmask_b32_e32 v151, v151, v152, vcc
	v_rsq_f32_e32 v151, v151
	s_nop 0
	v_mul_f32_e32 v152, 0x45800000, v151
	v_cndmask_b32_e32 v151, v151, v152, vcc
	s_add_u32 s52, s20, 0x100000
	s_addc_u32 s53, s21, 0
	v_mul_f32_e32 v60, v151, v60
	v_mul_f32_e32 v61, v151, v61
	v_mul_f32_e32 v62, v151, v62
	v_mul_f32_e32 v63, v151, v63
	v_mul_f32_e32 v56, v151, v56
	v_mul_f32_e32 v57, v151, v57
	v_mul_f32_e32 v58, v151, v58
	v_mul_f32_e32 v59, v151, v59
	v_mul_f32_e32 v60, v200, v60
	v_mul_f32_e32 v61, v201, v61
	v_mul_f32_e32 v62, v202, v62
	v_mul_f32_e32 v63, v203, v63
	v_mul_f32_e32 v56, v204, v56
	v_mul_f32_e32 v57, v205, v57
	v_mul_f32_e32 v58, v206, v58
	v_mul_f32_e32 v59, v207, v59
	global_store_dwordx4 v147, v[60:63], s[52:53] offset:0
	global_store_dwordx4 v147, v[56:59], s[52:53] offset:16
	v_mul_f32_e32 v52, v151, v52
	v_mul_f32_e32 v53, v151, v53
	v_mul_f32_e32 v54, v151, v54
	v_mul_f32_e32 v55, v151, v55
	v_mul_f32_e32 v48, v151, v48
	v_mul_f32_e32 v49, v151, v49
	v_mul_f32_e32 v50, v151, v50
	v_mul_f32_e32 v51, v151, v51
	v_mul_f32_e32 v52, v208, v52
	v_mul_f32_e32 v53, v209, v53
	v_mul_f32_e32 v54, v210, v54
	v_mul_f32_e32 v55, v211, v55
	v_mul_f32_e32 v48, v212, v48
	v_mul_f32_e32 v49, v213, v49
	v_mul_f32_e32 v50, v214, v50
	v_mul_f32_e32 v51, v215, v51
	global_store_dwordx4 v147, v[52:55], s[52:53] offset:512
	global_store_dwordx4 v147, v[48:51], s[52:53] offset:528
	s_waitcnt vmcnt(22)
	v_fmamk_f32 v151, v189, 0x3a000000, v160
	v_mul_f32_e32 v152, 0x4b800000, v151
	v_cmp_gt_f32_e32 vcc, s65, v151
	s_nop 1
	v_cndmask_b32_e32 v151, v151, v152, vcc
	v_rsq_f32_e32 v151, v151
	s_nop 0
	v_mul_f32_e32 v152, 0x45800000, v151
	v_cndmask_b32_e32 v151, v151, v152, vcc
	s_add_u32 s52, s20, 0x120000
	s_addc_u32 s53, s21, 0
	v_mul_f32_e32 v44, v151, v44
	v_mul_f32_e32 v45, v151, v45
	v_mul_f32_e32 v46, v151, v46
	v_mul_f32_e32 v47, v151, v47
	v_mul_f32_e32 v40, v151, v40
	v_mul_f32_e32 v41, v151, v41
	v_mul_f32_e32 v42, v151, v42
	v_mul_f32_e32 v43, v151, v43
	v_mul_f32_e32 v44, v200, v44
	v_mul_f32_e32 v45, v201, v45
	v_mul_f32_e32 v46, v202, v46
	v_mul_f32_e32 v47, v203, v47
	v_mul_f32_e32 v40, v204, v40
	v_mul_f32_e32 v41, v205, v41
	v_mul_f32_e32 v42, v206, v42
	v_mul_f32_e32 v43, v207, v43
	global_store_dwordx4 v147, v[44:47], s[52:53] offset:0
	global_store_dwordx4 v147, v[40:43], s[52:53] offset:16
	v_mul_f32_e32 v36, v151, v36
	v_mul_f32_e32 v37, v151, v37
	v_mul_f32_e32 v38, v151, v38
	v_mul_f32_e32 v39, v151, v39
	v_mul_f32_e32 v32, v151, v32
	v_mul_f32_e32 v33, v151, v33
	v_mul_f32_e32 v34, v151, v34
	v_mul_f32_e32 v35, v151, v35
	v_mul_f32_e32 v36, v208, v36
	v_mul_f32_e32 v37, v209, v37
	v_mul_f32_e32 v38, v210, v38
	v_mul_f32_e32 v39, v211, v39
	v_mul_f32_e32 v32, v212, v32
	v_mul_f32_e32 v33, v213, v33
	v_mul_f32_e32 v34, v214, v34
	v_mul_f32_e32 v35, v215, v35
	global_store_dwordx4 v147, v[36:39], s[52:53] offset:512
	global_store_dwordx4 v147, v[32:35], s[52:53] offset:528
	s_waitcnt vmcnt(25)
	v_fmamk_f32 v151, v190, 0x3a000000, v160
	v_mul_f32_e32 v152, 0x4b800000, v151
	v_cmp_gt_f32_e32 vcc, s65, v151
	s_nop 1
	v_cndmask_b32_e32 v151, v151, v152, vcc
	v_rsq_f32_e32 v151, v151
	s_nop 0
	v_mul_f32_e32 v152, 0x45800000, v151
	v_cndmask_b32_e32 v151, v151, v152, vcc
	s_add_u32 s52, s20, 0x140000
	s_addc_u32 s53, s21, 0
	v_mul_f32_e32 v28, v151, v28
	v_mul_f32_e32 v29, v151, v29
	v_mul_f32_e32 v30, v151, v30
	v_mul_f32_e32 v31, v151, v31
	v_mul_f32_e32 v24, v151, v24
	v_mul_f32_e32 v25, v151, v25
	v_mul_f32_e32 v26, v151, v26
	v_mul_f32_e32 v27, v151, v27
	v_mul_f32_e32 v28, v200, v28
	v_mul_f32_e32 v29, v201, v29
	v_mul_f32_e32 v30, v202, v30
	v_mul_f32_e32 v31, v203, v31
	v_mul_f32_e32 v24, v204, v24
	v_mul_f32_e32 v25, v205, v25
	v_mul_f32_e32 v26, v206, v26
	v_mul_f32_e32 v27, v207, v27
	global_store_dwordx4 v147, v[28:31], s[52:53] offset:0
	global_store_dwordx4 v147, v[24:27], s[52:53] offset:16
	v_mul_f32_e32 v20, v151, v20
	v_mul_f32_e32 v21, v151, v21
	v_mul_f32_e32 v22, v151, v22
	v_mul_f32_e32 v23, v151, v23
	v_mul_f32_e32 v16, v151, v16
	v_mul_f32_e32 v17, v151, v17
	v_mul_f32_e32 v18, v151, v18
	v_mul_f32_e32 v19, v151, v19
	v_mul_f32_e32 v20, v208, v20
	v_mul_f32_e32 v21, v209, v21
	v_mul_f32_e32 v22, v210, v22
	v_mul_f32_e32 v23, v211, v23
	v_mul_f32_e32 v16, v212, v16
	v_mul_f32_e32 v17, v213, v17
	v_mul_f32_e32 v18, v214, v18
	v_mul_f32_e32 v19, v215, v19
	global_store_dwordx4 v147, v[20:23], s[52:53] offset:512
	global_store_dwordx4 v147, v[16:19], s[52:53] offset:528
	s_waitcnt vmcnt(28)
	v_fmamk_f32 v151, v191, 0x3a000000, v160
	v_mul_f32_e32 v152, 0x4b800000, v151
	v_cmp_gt_f32_e32 vcc, s65, v151
	s_nop 1
	v_cndmask_b32_e32 v151, v151, v152, vcc
	v_rsq_f32_e32 v151, v151
	s_nop 0
	v_mul_f32_e32 v152, 0x45800000, v151
	v_cndmask_b32_e32 v151, v151, v152, vcc
	s_add_u32 s52, s20, 0x160000
	s_addc_u32 s53, s21, 0
	v_mul_f32_e32 v12, v151, v12
	v_mul_f32_e32 v13, v151, v13
	v_mul_f32_e32 v14, v151, v14
	v_mul_f32_e32 v15, v151, v15
	v_mul_f32_e32 v8, v151, v8
	v_mul_f32_e32 v9, v151, v9
	v_mul_f32_e32 v10, v151, v10
	v_mul_f32_e32 v11, v151, v11
	v_mul_f32_e32 v12, v200, v12
	v_mul_f32_e32 v13, v201, v13
	v_mul_f32_e32 v14, v202, v14
	v_mul_f32_e32 v15, v203, v15
	v_mul_f32_e32 v8, v204, v8
	v_mul_f32_e32 v9, v205, v9
	v_mul_f32_e32 v10, v206, v10
	v_mul_f32_e32 v11, v207, v11
	global_store_dwordx4 v147, v[12:15], s[52:53] offset:0
	global_store_dwordx4 v147, v[8:11], s[52:53] offset:16
	v_mul_f32_e32 v4, v151, v4
	v_mul_f32_e32 v5, v151, v5
	v_mul_f32_e32 v6, v151, v6
	v_mul_f32_e32 v7, v151, v7
	v_mul_f32_e32 v0, v151, v0
	v_mul_f32_e32 v1, v151, v1
	v_mul_f32_e32 v2, v151, v2
	v_mul_f32_e32 v3, v151, v3
	v_mul_f32_e32 v4, v208, v4
	v_mul_f32_e32 v5, v209, v5
	v_mul_f32_e32 v6, v210, v6
	v_mul_f32_e32 v7, v211, v7
	v_mul_f32_e32 v0, v212, v0
	v_mul_f32_e32 v1, v213, v1
	v_mul_f32_e32 v2, v214, v2
	v_mul_f32_e32 v3, v215, v3
	global_store_dwordx4 v147, v[4:7], s[52:53] offset:512
	global_store_dwordx4 v147, v[0:3], s[52:53] offset:528
	s_branch .Lp4_epi_end

.Lp4_epi_end:
	s_andn2_b64 vcc, exec, s[4:5]
	s_mov_b64 s[4:5], -1
	s_cbranch_vccnz .LBB0_780
	s_andn2_b64 vcc, exec, s[8:9]
	s_cbranch_vccnz .LBB0_779
	s_barrier
	s_branch .LBB0_779

.LBB0_811:
	s_cmp_lg_u32 s24, 0x100
	s_cbranch_scc1 .Lp4_keep_p5
	s_endpgm
